# diff-attn: row-max tree skipped on steady-state tiles (stale reference max kept while tile row-sums <= 2^16, else tile redone via classic max path; first tile classic)
# speedup vs baseline: 1.0558x; 1.0070x over previous
.LBB0_44:
	s_cmpk_gt_i32 s54, 0x7ff
	s_cbranch_scc1 .LBB0_43
	s_waitcnt vmcnt(10)
	v_mov_b32_e32 v54, v224
	s_ashr_i32 s55, s54, 5
	v_readfirstlane_b32 s0, v54
	s_sub_i32 s57, 63, s55
	s_ashr_i32 s0, s0, 1
	s_lshl_b32 s1, s57, 7
	s_and_b32 s52, s0, 0xffffffe0
	s_add_i32 s52, s52, s1
	s_bfe_u32 s56, s54, 0x10004
	s_and_b32 s48, s54, 15
	v_and_or_b32 v170, v54, 15, s52
	s_lshl_b32 s94, s56, 13
	s_lshl_b32 s0, s48, 7
	v_ashrrev_i32_e32 v171, 31, v170
	s_add_u32 s0, s13, s0
	v_lshl_add_u64 v[172:173], v[170:171], 0, s[94:95]
	s_addc_u32 s1, s14, 0
	v_and_b32_e32 v0, 16, v54
	v_lshlrev_b64 v[2:3], 11, v[172:173]
	v_cmp_eq_u32_e64 s[40:41], 0, v0
	s_waitcnt vmcnt(1)
	v_lshl_add_u64 v[14:15], s[0:1], 0, v[2:3]
	v_and_b32_e32 v0, 48, v54
	v_lshl_add_u64 v[6:7], v[14:15], 0, v[0:1]
	v_lshlrev_b64 v[10:11], 6, v[170:171]
	global_load_dwordx4 v[2:5], v[6:7], off offset:64
	s_nop 0
	global_load_dwordx4 v[6:9], v[6:7], off
	v_lshl_add_u64 v[22:23], s[4:5], 0, v[10:11]
	global_load_dwordx4 v[10:13], v[14:15], off
	s_nop 0
	global_load_dwordx4 v[14:17], v[14:15], off offset:16
	v_or_b32_e32 v176, 16, v170
	v_and_b32_e32 v55, 63, v54
	v_ashrrev_i32_e32 v177, 31, v176
	v_cmp_gt_u32_e32 vcc, 32, v55
	v_lshl_add_u64 v[174:175], v[176:177], 0, s[94:95]
	v_mov_b32_e32 v90, v1
	v_mov_b32_e32 v91, v1
	v_mov_b32_e32 v92, v1
	v_mov_b32_e32 v93, v1
	v_lshlrev_b32_e32 v193, 4, v54
	v_lshlrev_b32_e32 v197, 4, v55
	v_mov_b64_e32 v[70:71], v[90:91]
	v_mov_b64_e32 v[104:105], v[92:93]
	v_mov_b64_e32 v[66:67], v[90:91]
	v_mov_b64_e32 v[100:101], v[92:93]
	v_mov_b64_e32 v[58:59], v[90:91]
	v_mov_b64_e32 v[96:97], v[92:93]
	v_mov_b64_e32 v[86:87], v[90:91]
	v_mov_b64_e32 v[82:83], v[90:91]
	v_mov_b64_e32 v[78:79], v[90:91]
	v_mov_b64_e32 v[74:75], v[90:91]
	s_mov_b32 s49, 63
	s_mov_b32 s53, 0
	v_mov_b32_e32 v200, 0
	v_mov_b32_e32 v198, 0
	v_mov_b64_e32 v[72:73], v[92:93]
	v_mov_b64_e32 v[102:103], v[90:91]
	v_mov_b64_e32 v[68:69], v[92:93]
	v_mov_b64_e32 v[98:99], v[90:91]
	v_mov_b64_e32 v[60:61], v[92:93]
	v_mov_b64_e32 v[94:95], v[90:91]
	v_mov_b64_e32 v[88:89], v[92:93]
	v_mov_b64_e32 v[84:85], v[92:93]
	v_mov_b64_e32 v[80:81], v[92:93]
	v_mov_b64_e32 v[76:77], v[92:93]
	s_waitcnt vmcnt(1)
	v_lshlrev_b32_e32 v26, 16, v10
	s_waitcnt vmcnt(0)
	v_lshlrev_b32_e32 v27, 16, v14
	v_and_b32_e32 v29, 0xffff0000, v14
	v_and_b32_e32 v28, 0xffff0000, v10
	v_lshlrev_b32_e32 v31, 16, v15
	v_lshlrev_b32_e32 v30, 16, v11
	v_and_b32_e32 v33, 0xffff0000, v15
	v_and_b32_e32 v32, 0xffff0000, v11
	v_lshlrev_b32_e32 v35, 16, v16
	v_lshlrev_b32_e32 v34, 16, v12
	v_and_b32_e32 v37, 0xffff0000, v16
	v_and_b32_e32 v36, 0xffff0000, v12
	v_lshlrev_b32_e32 v39, 16, v17
	v_lshlrev_b32_e32 v38, 16, v13
	v_and_b32_e32 v41, 0xffff0000, v17
	v_and_b32_e32 v40, 0xffff0000, v13
	global_load_dwordx4 v[10:13], v[22:23], off offset:48
	global_load_dwordx4 v[14:17], v[22:23], off offset:16
	global_load_dwordx4 v[18:21], v[22:23], off offset:32
	s_nop 0
	global_load_dwordx4 v[22:25], v[22:23], off
	s_waitcnt vmcnt(1)
	v_mov_b32_e32 v43, v18
	s_waitcnt vmcnt(0)
	v_mov_b32_e32 v42, v22
	v_pk_mul_f32 v[42:43], v[42:43], v[26:27]
	s_nop 0
	v_sub_f32_e32 v44, v42, v43
	v_mov_b32_e32 v42, v18
	v_mov_b32_e32 v43, v22
	v_pk_mul_f32 v[26:27], v[42:43], v[26:27]
	v_mov_b32_e32 v22, v19
	v_add_f32_e32 v18, v26, v27
	v_cndmask_b32_e64 v42, v18, v44, s[40:41]
	v_mov_b32_e32 v18, v23
	v_pk_mul_f32 v[26:27], v[18:19], v[28:29]
	v_pk_mul_f32 v[18:19], v[22:23], v[28:29]
	v_sub_f32_e32 v26, v26, v27
	v_add_f32_e32 v18, v19, v18
	v_cndmask_b32_e64 v22, v18, v26, s[40:41]
	v_mov_b32_e32 v18, v24
	v_mov_b32_e32 v19, v20
	v_pk_mul_f32 v[18:19], v[18:19], v[30:31]
	s_nop 0
	v_sub_f32_e32 v23, v18, v19
	v_mov_b32_e32 v18, v20
	v_mov_b32_e32 v19, v24
	v_pk_mul_f32 v[18:19], v[18:19], v[30:31]
	v_mov_b32_e32 v20, v25
	v_add_f32_e32 v18, v19, v18
	v_cndmask_b32_e64 v23, v18, v23, s[40:41]
	v_pk_mul_f32 v[18:19], v[20:21], v[32:33]
	v_mov_b32_e32 v24, v21
	v_sub_f32_e32 v20, v18, v19
	v_pk_mul_f32 v[18:19], v[24:25], v[32:33]
	s_nop 0
	v_add_f32_e32 v18, v19, v18
	v_cndmask_b32_e64 v20, v18, v20, s[40:41]
	v_mov_b32_e32 v18, v14
	v_mov_b32_e32 v19, v10
	v_pk_mul_f32 v[18:19], v[18:19], v[34:35]
	s_nop 0
	v_sub_f32_e32 v21, v18, v19
	v_mov_b32_e32 v18, v10
	v_mov_b32_e32 v19, v14
	v_pk_mul_f32 v[18:19], v[18:19], v[34:35]
	v_mov_b32_e32 v14, v11
	v_add_f32_e32 v10, v19, v18
	v_cndmask_b32_e64 v21, v10, v21, s[40:41]
	v_mov_b32_e32 v10, v15
	v_pk_mul_f32 v[18:19], v[10:11], v[36:37]
	v_pk_mul_f32 v[10:11], v[14:15], v[36:37]
	v_sub_f32_e32 v18, v18, v19
	v_add_f32_e32 v10, v11, v10
	v_cndmask_b32_e64 v14, v10, v18, s[40:41]
	v_mov_b32_e32 v10, v16
	v_mov_b32_e32 v11, v12
	v_pk_mul_f32 v[10:11], v[10:11], v[38:39]
	v_lshlrev_b64 v[18:19], 6, v[176:177]
	v_sub_f32_e32 v15, v10, v11
	v_mov_b32_e32 v10, v12
	v_mov_b32_e32 v11, v16
	v_pk_mul_f32 v[10:11], v[10:11], v[38:39]
	v_mov_b32_e32 v12, v17
	v_add_f32_e32 v10, v11, v10
	v_cndmask_b32_e64 v15, v10, v15, s[40:41]
	v_pk_mul_f32 v[10:11], v[12:13], v[40:41]
	v_mov_b32_e32 v16, v13
	v_sub_f32_e32 v12, v10, v11
	v_pk_mul_f32 v[10:11], v[16:17], v[40:41]
	v_cvt_pk_bf16_f32 v13, v21, v14
	v_add_f32_e32 v10, v11, v10
	v_cndmask_b32_e64 v10, v10, v12, s[40:41]
	v_cvt_pk_bf16_f32 v11, v42, v22
	v_cvt_pk_bf16_f32 v10, v15, v10
	v_cndmask_b32_e32 v9, v9, v10, vcc
	v_cndmask_b32_e32 v6, v6, v11, vcc
	v_lshlrev_b64 v[10:11], 11, v[174:175]
	v_cvt_pk_bf16_f32 v12, v23, v20
	v_lshl_add_u64 v[22:23], s[0:1], 0, v[10:11]
	v_lshl_add_u64 v[14:15], v[22:23], 0, v[0:1]
	v_cndmask_b32_e32 v8, v8, v13, vcc
	v_cndmask_b32_e32 v7, v7, v12, vcc
	global_load_dwordx4 v[10:13], v[14:15], off offset:64
	s_nop 0
	global_load_dwordx4 v[14:17], v[14:15], off
	v_lshl_add_u64 v[30:31], s[4:5], 0, v[18:19]
	global_load_dwordx4 v[18:21], v[22:23], off
	s_nop 0
	global_load_dwordx4 v[22:25], v[22:23], off offset:16
	s_waitcnt vmcnt(1)
	v_lshlrev_b32_e32 v48, 16, v18
	s_waitcnt vmcnt(0)
	v_lshlrev_b32_e32 v49, 16, v22
	v_and_b32_e32 v47, 0xffff0000, v22
	v_and_b32_e32 v46, 0xffff0000, v18
	v_lshlrev_b32_e32 v45, 16, v23
	v_lshlrev_b32_e32 v44, 16, v19
	v_and_b32_e32 v43, 0xffff0000, v23
	v_and_b32_e32 v42, 0xffff0000, v19
	v_lshlrev_b32_e32 v41, 16, v24
	v_lshlrev_b32_e32 v40, 16, v20
	v_and_b32_e32 v39, 0xffff0000, v24
	v_and_b32_e32 v38, 0xffff0000, v20
	v_lshlrev_b32_e32 v37, 16, v25
	v_lshlrev_b32_e32 v36, 16, v21
	v_and_b32_e32 v35, 0xffff0000, v25
	v_and_b32_e32 v34, 0xffff0000, v21
	global_load_dwordx4 v[18:21], v[30:31], off offset:48
	global_load_dwordx4 v[22:25], v[30:31], off offset:16
	global_load_dwordx4 v[26:29], v[30:31], off offset:32
	s_nop 0
	global_load_dwordx4 v[30:33], v[30:31], off
	s_barrier
	s_waitcnt vmcnt(1)
	v_mov_b32_e32 v51, v26
	s_waitcnt vmcnt(0)
	v_mov_b32_e32 v50, v30
	v_pk_mul_f32 v[50:51], v[50:51], v[48:49]
	s_nop 0
	v_sub_f32_e32 v0, v50, v51
	v_mov_b32_e32 v50, v26
	v_mov_b32_e32 v51, v30
	v_pk_mul_f32 v[48:49], v[50:51], v[48:49]
	v_mov_b32_e32 v30, v27
	v_add_f32_e32 v26, v48, v49
	v_cndmask_b32_e64 v0, v26, v0, s[40:41]
	v_mov_b32_e32 v26, v31
	v_pk_mul_f32 v[48:49], v[26:27], v[46:47]
	v_pk_mul_f32 v[26:27], v[30:31], v[46:47]
	v_sub_f32_e32 v48, v48, v49
	v_add_f32_e32 v26, v27, v26
	v_cndmask_b32_e64 v30, v26, v48, s[40:41]
	v_mov_b32_e32 v26, v32
	v_mov_b32_e32 v27, v28
	v_pk_mul_f32 v[26:27], v[26:27], v[44:45]
	v_cvt_pk_bf16_f32 v0, v0, v30
	v_sub_f32_e32 v31, v26, v27
	v_mov_b32_e32 v26, v28
	v_mov_b32_e32 v27, v32
	v_pk_mul_f32 v[26:27], v[26:27], v[44:45]
	v_mov_b32_e32 v28, v33
	v_add_f32_e32 v26, v27, v26
	v_cndmask_b32_e64 v31, v26, v31, s[40:41]
	v_pk_mul_f32 v[26:27], v[28:29], v[42:43]
	v_mov_b32_e32 v32, v29
	v_sub_f32_e32 v28, v26, v27
	v_pk_mul_f32 v[26:27], v[32:33], v[42:43]
	v_cndmask_b32_e32 v14, v14, v0, vcc
	v_add_f32_e32 v26, v27, v26
	v_cndmask_b32_e64 v28, v26, v28, s[40:41]
	v_mov_b32_e32 v26, v22
	v_mov_b32_e32 v27, v18
	v_pk_mul_f32 v[26:27], v[26:27], v[40:41]
	v_mov_b64_e32 v[46:47], v[90:91]
	v_sub_f32_e32 v29, v26, v27
	v_mov_b32_e32 v26, v18
	v_mov_b32_e32 v27, v22
	v_pk_mul_f32 v[26:27], v[26:27], v[40:41]
	v_mov_b32_e32 v22, v19
	v_add_f32_e32 v18, v27, v26
	v_cndmask_b32_e64 v29, v18, v29, s[40:41]
	v_mov_b32_e32 v18, v23
	v_pk_mul_f32 v[26:27], v[18:19], v[38:39]
	v_pk_mul_f32 v[18:19], v[22:23], v[38:39]
	v_sub_f32_e32 v26, v26, v27
	v_add_f32_e32 v18, v19, v18
	v_cndmask_b32_e64 v22, v18, v26, s[40:41]
	v_mov_b32_e32 v18, v24
	v_mov_b32_e32 v19, v20
	v_pk_mul_f32 v[18:19], v[18:19], v[36:37]
	v_lshlrev_b32_e32 v26, 3, v54
	v_sub_f32_e32 v23, v18, v19
	v_mov_b32_e32 v18, v20
	v_mov_b32_e32 v19, v24
	v_pk_mul_f32 v[18:19], v[18:19], v[36:37]
	v_mov_b32_e32 v20, v25
	v_add_f32_e32 v18, v19, v18
	v_cndmask_b32_e64 v23, v18, v23, s[40:41]
	v_pk_mul_f32 v[18:19], v[20:21], v[34:35]
	v_mov_b32_e32 v24, v21
	v_sub_f32_e32 v20, v18, v19
	v_pk_mul_f32 v[18:19], v[24:25], v[34:35]
	v_ashrrev_i32_e32 v27, 31, v26
	v_add_f32_e32 v18, v19, v18
	v_cndmask_b32_e64 v18, v18, v20, s[40:41]
	s_lshl_b32 s40, s54, 20
	v_cvt_pk_bf16_f32 v20, v29, v22
	s_and_b32 s0, s40, 0x1f00000
	v_add_u32_e32 v22, 0x800, v26
	v_cvt_pk_bf16_f32 v18, v23, v18
	s_add_u32 s0, s15, s0
	v_ashrrev_i32_e32 v23, 31, v22
	v_cvt_pk_bf16_f32 v19, v31, v28
	s_addc_u32 s1, s44, 0
	v_lshlrev_b64 v[28:29], 1, v[26:27]
	v_lshlrev_b64 v[34:35], 1, v[22:23]
	v_cndmask_b32_e32 v17, v17, v18, vcc
	v_cndmask_b32_e32 v15, v15, v19, vcc
	v_lshl_add_u64 v[18:19], s[0:1], 0, v[28:29]
	v_lshl_add_u64 v[22:23], s[0:1], 0, v[34:35]
	s_and_b32 s0, s40, 0xe00000
	s_lshl_b32 s1, s56, 24
	s_lshl_b32 s41, s57, 1
	s_or_b32 s40, s1, s0
	s_add_u32 s0, s45, s40
	s_addc_u32 s1, s46, 0
	v_lshl_add_u64 v[30:31], s[0:1], 0, v[28:29]
	v_lshl_add_u64 v[36:37], s[0:1], 0, v[34:35]
	global_load_dwordx4 v[30:33], v[30:31], off
	v_cndmask_b32_e32 v16, v16, v20, vcc
	global_load_dwordx4 v[42:45], v[36:37], off
	v_add_u32_e32 v36, 0x1000, v26
	v_ashrrev_i32_e32 v37, 31, v36
	v_add_u32_e32 v26, 0x1800, v26
	v_lshlrev_b64 v[36:37], 1, v[36:37]
	v_ashrrev_i32_e32 v27, 31, v26
	v_lshl_add_u64 v[38:39], s[0:1], 0, v[36:37]
	v_lshlrev_b64 v[26:27], 1, v[26:27]
	global_load_dwordx4 v[50:53], v[38:39], off
	v_lshl_add_u64 v[38:39], s[0:1], 0, v[26:27]
	global_load_dwordx4 v[18:21], v[18:19], off
	s_add_i32 s0, s41, 2
	global_load_dwordx4 v[22:25], v[22:23], off
	v_readlane_b32 s1, v254, 13
	global_load_dwordx4 v[62:65], v[38:39], off
	s_add_u32 s40, s1, s40
	v_readlane_b32 s1, v254, 14
	v_cmp_lt_i32_e32 vcc, v247, v214
	s_addc_u32 s41, s1, 0
	s_and_b32 s1, s54, 31
	v_cndmask_b32_e32 v0, v225, v247, vcc
	v_cmp_lt_i32_e32 vcc, v246, v214
	v_mov_b32_e32 v180, v34
	v_mov_b32_e32 v181, v28
	v_mov_b32_e32 v182, v36
	s_mov_b64 s[98:99], s[40:41]
	v_mov_b32_e32 v184, v26
	s_lshl_b32 s1, s1, 20
	v_readlane_b32 s40, v254, 15
	v_lshlrev_b32_e32 v177, 2, v0
	v_cndmask_b32_e32 v0, v225, v246, vcc
	s_add_u32 s40, s40, s1
	v_readlane_b32 s1, v254, 16
	v_lshlrev_b32_e32 v171, 2, v0
	v_lshrrev_b32_e32 v0, 2, v54
	s_addc_u32 s41, s1, 0
	v_and_b32_e32 v192, 12, v0
	s_mov_b64 s[2:3], s[40:41]
	s_lshl_b32 s1, s55, 1
	v_mov_b32_e32 v0, v1
	v_mov_b64_e32 v[54:55], v[90:91]
	v_mov_b64_e32 v[38:39], v[90:91]
	v_mov_b64_e32 v[34:35], v[90:91]
	v_mov_b64_e32 v[26:27], v[90:91]
	s_sub_i32 s1, 0, s1
	s_movk_i32 s54, 0xff80
	v_mov_b64_e32 v[56:57], v[92:93]
	v_mov_b64_e32 v[48:49], v[92:93]
	v_mov_b64_e32 v[40:41], v[92:93]
	v_mov_b64_e32 v[36:37], v[92:93]
	v_mov_b64_e32 v[28:29], v[92:93]
	v_mov_b64_e32 v[178:179], v[0:1]
	s_waitcnt vmcnt(0)
	ds_write_b128 v193, v[18:21]
	ds_write_b128 v193, v[22:25] offset:4096
	ds_write_b128 v193, v[30:33] offset:8192
	ds_write_b128 v193, v[42:45] offset:12288
	ds_write_b128 v193, v[50:53] offset:16384
	ds_write_b128 v193, v[62:65] offset:20480
	v_mov_b32_e32 v18, 0
	v_mov_b32_e32 v19, 0
	v_mov_b32_e32 v20, 0
	v_mov_b32_e32 v21, 0
	v_mov_b32_e32 v22, 0
	v_mov_b32_e32 v23, 0
	v_mov_b32_e32 v24, 0
	v_mov_b32_e32 v25, 0
	s_mov_b32 s101, 1

.LBB0_50:
	s_cmp_eq_u32 s101, 0
	s_cbranch_scc1 .LBB0_52
	v_max3_f32 v194, v166, v167, v168
	v_max3_f32 v195, v169, v162, v163
	v_max3_f32 v196, v164, v165, v158
	v_max3_f32 v194, v194, v159, v160
	v_max3_f32 v195, v195, v161, v154
	v_max3_f32 v196, v196, v155, v156
	v_max3_f32 v194, v194, v195, v157
	v_max_f32_e32 v194, v194, v196
	v_max3_f32 v195, v150, v151, v152
	v_max3_f32 v196, v153, v146, v147
	v_max3_f32 v199, v148, v149, v142
	v_max3_f32 v195, v195, v143, v144
	v_max3_f32 v196, v196, v145, v138
	v_max3_f32 v199, v199, v139, v140
	v_max3_f32 v195, v195, v196, v141
	v_max_f32_e32 v195, v195, v199
	v_mov_b32_e32 v196, v194
	v_mov_b32_e32 v199, v195
	s_nop 1
	v_permlane16_swap_b32_e32 v194, v196
	v_permlane16_swap_b32_e32 v195, v199
	v_max_f32_e32 v194, v194, v196
	v_max_f32_e32 v195, v195, v199
	v_mov_b32_e32 v196, v194
	v_mov_b32_e32 v199, v195
	s_nop 1
	v_permlane32_swap_b32_e32 v194, v196
	v_permlane32_swap_b32_e32 v195, v199
	v_max_f32_e32 v195, v195, v199
	v_max_f32_e32 v194, v194, v196
	s_cmpk_eq_i32 s54, 0xff80
	s_cbranch_scc1 .Lmy_first
	v_max_f32_e32 v196, v194, v195
	v_cmp_lt_f32_e32 vcc, 0x41000000, v196
	s_and_b64 vcc, exec, vcc
	s_cbranch_vccz .LBB0_52
	v_max_f32_e32 v199, 0, v194
	v_max_f32_e32 v201, 0, v195
	v_sub_f32_e32 v194, 0, v199
	v_exp_f32_e32 v194, v194
	s_nop 0
	v_pk_mul_f32 v[92:93], v[92:93], v[194:195] op_sel_hi:[1,0]
	v_pk_mul_f32 v[90:91], v[90:91], v[194:195] op_sel_hi:[1,0]
	v_pk_mul_f32 v[104:105], v[104:105], v[194:195] op_sel_hi:[1,0]
	v_pk_mul_f32 v[102:103], v[102:103], v[194:195] op_sel_hi:[1,0]
	v_pk_mul_f32 v[100:101], v[100:101], v[194:195] op_sel_hi:[1,0]
	v_pk_mul_f32 v[98:99], v[98:99], v[194:195] op_sel_hi:[1,0]
	v_pk_mul_f32 v[96:97], v[96:97], v[194:195] op_sel_hi:[1,0]
	v_pk_mul_f32 v[94:95], v[94:95], v[194:195] op_sel_hi:[1,0]
	v_pk_mul_f32 v[88:89], v[88:89], v[194:195] op_sel_hi:[1,0]
	v_pk_mul_f32 v[86:87], v[86:87], v[194:195] op_sel_hi:[1,0]
	v_pk_mul_f32 v[84:85], v[84:85], v[194:195] op_sel_hi:[1,0]
	v_pk_mul_f32 v[82:83], v[82:83], v[194:195] op_sel_hi:[1,0]
	v_pk_mul_f32 v[80:81], v[80:81], v[194:195] op_sel_hi:[1,0]
	v_pk_mul_f32 v[78:79], v[78:79], v[194:195] op_sel_hi:[1,0]
	v_pk_mul_f32 v[76:77], v[76:77], v[194:195] op_sel_hi:[1,0]
	v_pk_mul_f32 v[74:75], v[74:75], v[194:195] op_sel_hi:[1,0]
	v_sub_f32_e32 v195, 0, v201
	v_exp_f32_e32 v195, v195
	s_nop 0
	v_pk_mul_f32 v[178:179], v[178:179], v[194:195]
	v_mov_b32_e32 v194, v195
	v_pk_mul_f32 v[72:73], v[72:73], v[194:195] op_sel_hi:[1,0]
	v_pk_mul_f32 v[70:71], v[70:71], v[194:195] op_sel_hi:[1,0]
	v_pk_mul_f32 v[68:69], v[68:69], v[194:195] op_sel_hi:[1,0]
	v_pk_mul_f32 v[66:67], v[66:67], v[194:195] op_sel_hi:[1,0]
	v_pk_mul_f32 v[60:61], v[60:61], v[194:195] op_sel_hi:[1,0]
	v_pk_mul_f32 v[58:59], v[58:59], v[194:195] op_sel_hi:[1,0]
	v_pk_mul_f32 v[56:57], v[56:57], v[194:195] op_sel_hi:[1,0]
	v_pk_mul_f32 v[54:55], v[54:55], v[194:195] op_sel_hi:[1,0]
	v_pk_mul_f32 v[48:49], v[48:49], v[194:195] op_sel_hi:[1,0]
	v_pk_mul_f32 v[46:47], v[46:47], v[194:195] op_sel_hi:[1,0]
	v_pk_mul_f32 v[40:41], v[40:41], v[194:195] op_sel_hi:[1,0]
	v_pk_mul_f32 v[38:39], v[38:39], v[194:195] op_sel_hi:[1,0]
	v_pk_mul_f32 v[36:37], v[36:37], v[194:195] op_sel_hi:[1,0]
	v_pk_mul_f32 v[34:35], v[34:35], v[194:195] op_sel_hi:[1,0]
	v_pk_mul_f32 v[28:29], v[28:29], v[194:195] op_sel_hi:[1,0]
	v_pk_mul_f32 v[26:27], v[26:27], v[194:195] op_sel_hi:[1,0]

.LBB0_52:
	v_exp_f32_e32 v194, v167
	v_exp_f32_e32 v168, v168
	v_exp_f32_e32 v204, v163
	v_exp_f32_e32 v208, v159
	v_exp_f32_e32 v166, v166
	v_exp_f32_e32 v202, v169
	v_exp_f32_e32 v164, v164
	v_exp_f32_e32 v160, v160
	v_exp_f32_e32 v212, v155
	v_exp_f32_e32 v167, v150
	v_exp_f32_e32 v216, v157
	v_exp_f32_e32 v195, v151
	v_exp_f32_e32 v169, v152
	v_exp_f32_e32 v203, v153
	v_exp_f32_e32 v162, v162
	v_exp_f32_e32 v206, v165
	v_exp_f32_e32 v163, v146
	v_pk_add_f32 v[150:151], v[166:167], 0 op_sel_hi:[1,0]
	v_exp_f32_e32 v205, v147
	v_pk_add_f32 v[150:151], v[194:195], v[150:151]
	v_exp_f32_e32 v165, v148
	v_pk_add_f32 v[150:151], v[168:169], v[150:151]
	v_exp_f32_e32 v207, v149
	v_pk_add_f32 v[150:151], v[202:203], v[150:151]
	v_exp_f32_e32 v158, v158
	v_exp_f32_e32 v210, v161
	v_pk_add_f32 v[150:151], v[162:163], v[150:151]
	v_exp_f32_e32 v159, v142
	v_pk_add_f32 v[150:151], v[204:205], v[150:151]
	v_exp_f32_e32 v209, v143
	v_exp_f32_e32 v156, v156
	v_pk_add_f32 v[150:151], v[164:165], v[150:151]
	v_exp_f32_e32 v161, v144
	v_exp_f32_e32 v155, v138
	v_pk_add_f32 v[150:151], v[206:207], v[150:151]
	v_exp_f32_e32 v211, v145
	v_exp_f32_e32 v213, v139
	v_exp_f32_e32 v154, v154
	v_exp_f32_e32 v157, v140
	v_pk_add_f32 v[138:139], v[158:159], v[150:151]
	v_pk_add_f32 v[138:139], v[208:209], v[138:139]
	v_exp_f32_e32 v217, v141
	v_pk_add_f32 v[138:139], v[160:161], v[138:139]
	v_cvt_pk_bf16_f32 v146, v166, v194
	v_pk_add_f32 v[138:139], v[210:211], v[138:139]
	v_cvt_pk_bf16_f32 v147, v168, v202
	v_pk_add_f32 v[138:139], v[154:155], v[138:139]
	v_cvt_pk_bf16_f32 v148, v162, v204
	v_pk_add_f32 v[138:139], v[212:213], v[138:139]
	v_cvt_pk_bf16_f32 v149, v164, v206
	v_pk_add_f32 v[138:139], v[156:157], v[138:139]
	v_cvt_pk_bf16_f32 v140, v154, v212
	v_pk_add_f32 v[142:143], v[216:217], v[138:139]
	v_cvt_pk_bf16_f32 v138, v158, v208
	v_cvt_pk_bf16_f32 v139, v160, v210
	v_cvt_pk_bf16_f32 v141, v156, v216
	v_max_f32_e32 v196, v142, v143
	v_cmp_lt_f32_e32 vcc, 0x47800000, v196
	s_cbranch_vccnz .Lmy_redo
	v_pk_add_f32 v[178:179], v[142:143], v[178:179]
	v_cvt_pk_bf16_f32 v142, v167, v195
	v_cvt_pk_bf16_f32 v143, v169, v203
	v_cvt_pk_bf16_f32 v144, v163, v205
	v_cvt_pk_bf16_f32 v145, v165, v207
	v_cvt_pk_bf16_f32 v150, v159, v209
	v_cvt_pk_bf16_f32 v151, v161, v211
	v_cvt_pk_bf16_f32 v152, v155, v213
	v_cvt_pk_bf16_f32 v153, v157, v217
	ds_read_b128 v[154:157], v0 offset:16384
	ds_read_b128 v[158:161], v0 offset:17408
	ds_read_b128 v[162:165], v0 offset:18432
	ds_read_b128 v[166:169], v0 offset:19456
	ds_read_b128 v[202:205], v0 offset:20480
	ds_read_b128 v[206:209], v0 offset:21504
	ds_read_b128 v[210:213], v0 offset:22528
	ds_read_b128 v[216:219], v0 offset:23552
	s_waitcnt lgkmcnt(8)
	v_mfma_f32_16x16x32_bf16 v[90:93], v[134:137], v[146:149], v[90:93]
	v_mfma_f32_16x16x32_bf16 v[70:73], v[134:137], v[142:145], v[70:73]
	v_mfma_f32_16x16x32_bf16 v[102:105], v[126:129], v[146:149], v[102:105]
	v_mfma_f32_16x16x32_bf16 v[66:69], v[126:129], v[142:145], v[66:69]
	v_mfma_f32_16x16x32_bf16 v[98:101], v[118:121], v[146:149], v[98:101]
	v_mfma_f32_16x16x32_bf16 v[58:61], v[118:121], v[142:145], v[58:61]
	v_mfma_f32_16x16x32_bf16 v[94:97], v[110:113], v[146:149], v[94:97]
	v_mfma_f32_16x16x32_bf16 v[54:57], v[110:113], v[142:145], v[54:57]
	s_waitcnt lgkmcnt(7)
	v_mfma_f32_16x16x32_bf16 v[86:89], v[154:157], v[146:149], v[86:89]
	v_mfma_f32_16x16x32_bf16 v[46:49], v[154:157], v[142:145], v[46:49]
	s_waitcnt lgkmcnt(5)
	v_mfma_f32_16x16x32_bf16 v[82:85], v[162:165], v[146:149], v[82:85]
	v_mfma_f32_16x16x32_bf16 v[38:41], v[162:165], v[142:145], v[38:41]
	s_waitcnt lgkmcnt(3)
	v_mfma_f32_16x16x32_bf16 v[78:81], v[202:205], v[146:149], v[78:81]
	v_mfma_f32_16x16x32_bf16 v[34:37], v[202:205], v[142:145], v[34:37]
	s_waitcnt lgkmcnt(1)
	v_mfma_f32_16x16x32_bf16 v[74:77], v[210:213], v[146:149], v[74:77]
	v_mfma_f32_16x16x32_bf16 v[26:29], v[210:213], v[142:145], v[26:29]
	v_mfma_f32_16x16x32_bf16 v[90:93], v[130:133], v[138:141], v[90:93]
	v_mfma_f32_16x16x32_bf16 v[70:73], v[130:133], v[150:153], v[70:73]
	v_mfma_f32_16x16x32_bf16 v[102:105], v[122:125], v[138:141], v[102:105]
	v_mfma_f32_16x16x32_bf16 v[66:69], v[122:125], v[150:153], v[66:69]
	v_mfma_f32_16x16x32_bf16 v[98:101], v[114:117], v[138:141], v[98:101]
	v_mfma_f32_16x16x32_bf16 v[58:61], v[114:117], v[150:153], v[58:61]
	v_mfma_f32_16x16x32_bf16 v[94:97], v[106:109], v[138:141], v[94:97]
	v_mfma_f32_16x16x32_bf16 v[54:57], v[106:109], v[150:153], v[54:57]
	v_mfma_f32_16x16x32_bf16 v[86:89], v[158:161], v[138:141], v[86:89]
	v_mfma_f32_16x16x32_bf16 v[46:49], v[158:161], v[150:153], v[46:49]
	v_mfma_f32_16x16x32_bf16 v[82:85], v[166:169], v[138:141], v[82:85]
	v_mfma_f32_16x16x32_bf16 v[38:41], v[166:169], v[150:153], v[38:41]
	v_mfma_f32_16x16x32_bf16 v[78:81], v[206:209], v[138:141], v[78:81]
	v_mfma_f32_16x16x32_bf16 v[34:37], v[206:209], v[150:153], v[34:37]
	s_waitcnt lgkmcnt(0)
	v_mfma_f32_16x16x32_bf16 v[74:77], v[216:219], v[138:141], v[74:77]
	v_mfma_f32_16x16x32_bf16 v[26:29], v[216:219], v[150:153], v[26:29]
	s_xor_b32 s53, s53, 1
	s_add_i32 s49, s49, 64
	s_add_i32 s54, s54, 1
	s_add_u32 s98, s98, 0x4000
	s_addc_u32 s99, s99, 0
	s_add_u32 s2, s2, 0x2000
	s_addc_u32 s3, s3, 0
	s_cmp_lg_u32 s1, s54
	s_cbranch_scc0 .LBB0_42
	s_mov_b32 s101, 0
	s_branch .LBB0_46
.Lmy_redo:
	s_mov_b32 s101, 1
	s_mul_i32 s40, s53, 0x6000
	s_branch .LBB0_48
